# attention row-max: v_max(x,x) canonicalisations of MFMA outputs dropped in the lat-A and lat-B instantiations (identical results for non-signalling inputs)
# speedup vs baseline: 1.0024x; 1.0024x over previous
.LBB0_206:
	s_mul_i32 s2, s38, 0x5000
	v_lshl_or_b32 v0, v209, 1, s2
	v_lshl_add_u32 v220, v218, 1, v0
	ds_read_b128 v[4:7], v220
	v_lshl_add_u32 v14, v217, 1, v0
	ds_read_b128 v[8:11], v14
	v_lshl_add_u32 v221, v216, 1, v0
	v_lshl_add_u32 v13, v215, 1, v0
	v_or_b32_e32 v219, s2, v209
	v_lshl_add_u32 v15, v214, 1, v219
	v_lshl_add_u32 v12, v213, 1, v219
	v_cmp_lt_i32_e32 vcc, v180, v182
	s_waitcnt lgkmcnt(0)
	v_mfma_f32_32x32x16_bf16 v[96:111], v[4:7], v[152:155], 0
	ds_read_b128 v[222:225], v12 offset:16384
	v_cndmask_b32_e32 v0, v179, v180, vcc
	v_lshlrev_b32_e32 v0, 2, v0
	v_mfma_f32_32x32x16_bf16 v[80:95], v[4:7], v[156:159], 0
	ds_read_b128 v[4:7], v221
	v_mfma_f32_32x32x16_bf16 v[96:111], v[8:11], v[140:143], v[96:111]
	v_mfma_f32_32x32x16_bf16 v[80:95], v[8:11], v[148:151], v[80:95]
	ds_read_b128 v[8:11], v13
	s_waitcnt lgkmcnt(0)
	v_mfma_f32_32x32x16_bf16 v[96:111], v[4:7], v[136:139], v[96:111]
	v_mfma_f32_32x32x16_bf16 v[80:95], v[4:7], v[144:147], v[80:95]
	ds_read_b128 v[4:7], v15 offset:16384
	v_mfma_f32_32x32x16_bf16 v[96:111], v[8:11], v[124:127], v[96:111]
	s_waitcnt lgkmcnt(0)
	v_mfma_f32_32x32x16_bf16 v[96:111], v[4:7], v[120:123], v[96:111]
	v_mfma_f32_32x32x16_bf16 v[96:111], v[222:225], v[112:115], v[96:111]
	v_mfma_f32_32x32x16_bf16 v[80:95], v[8:11], v[132:135], v[80:95]
	s_nop 10
	v_max_f32_e32 v188, v97, v97
	v_max_f32_e32 v8, v188, v96
	v_max3_f32 v8, v8, v98, v99
	v_max3_f32 v8, v8, v100, v101
	v_max3_f32 v8, v8, v102, v103
	v_max3_f32 v8, v8, v104, v105
	v_mfma_f32_32x32x16_bf16 v[80:95], v[4:7], v[128:131], v[80:95]
	v_max3_f32 v8, v8, v106, v107
	v_max3_f32 v4, v8, v108, v109
	v_max3_f32 v4, v4, v110, v111
	v_mov_b32_e32 v5, v4
	s_nop 1
	v_permlane32_swap_b32_e32 v5, v4
	s_nop 1
	s_waitcnt lgkmcnt(0)
	v_mfma_f32_32x32x16_bf16 v[80:95], v[222:225], v[116:119], v[80:95]
	v_max_f32_e32 v4, v4, v5
	v_add_f32_e32 v5, 0x41000000, v1
	v_cmp_gt_f32_e32 vcc, v4, v5
	s_cbranch_vccz .LBB0_208
	v_max_f32_e32 v5, v1, v4
	v_sub_f32_e32 v1, v1, v5
	v_exp_f32_e32 v4, v1
	v_mov_b32_e32 v1, v5
	v_mul_f32_e32 v3, v3, v4
	v_pk_mul_f32 v[78:79], v[78:79], v[4:5] op_sel_hi:[1,0]
	v_pk_mul_f32 v[76:77], v[76:77], v[4:5] op_sel_hi:[1,0]
	v_pk_mul_f32 v[74:75], v[74:75], v[4:5] op_sel_hi:[1,0]
	v_pk_mul_f32 v[72:73], v[72:73], v[4:5] op_sel_hi:[1,0]
	v_pk_mul_f32 v[70:71], v[70:71], v[4:5] op_sel_hi:[1,0]
	v_pk_mul_f32 v[68:69], v[68:69], v[4:5] op_sel_hi:[1,0]
	v_pk_mul_f32 v[66:67], v[66:67], v[4:5] op_sel_hi:[1,0]
	v_pk_mul_f32 v[64:65], v[64:65], v[4:5] op_sel_hi:[1,0]
	v_pk_mul_f32 v[62:63], v[62:63], v[4:5] op_sel_hi:[1,0]
	v_pk_mul_f32 v[60:61], v[60:61], v[4:5] op_sel_hi:[1,0]
	v_pk_mul_f32 v[58:59], v[58:59], v[4:5] op_sel_hi:[1,0]
	v_pk_mul_f32 v[56:57], v[56:57], v[4:5] op_sel_hi:[1,0]
	v_pk_mul_f32 v[54:55], v[54:55], v[4:5] op_sel_hi:[1,0]
	v_pk_mul_f32 v[52:53], v[52:53], v[4:5] op_sel_hi:[1,0]
	v_pk_mul_f32 v[50:51], v[50:51], v[4:5] op_sel_hi:[1,0]
	v_pk_mul_f32 v[48:49], v[48:49], v[4:5] op_sel_hi:[1,0]
.LBB0_208:
	s_nop 7
	v_max_f32_e32 v4, v80, v81
	v_max3_f32 v4, v4, v82, v83
	v_max3_f32 v4, v4, v84, v85
	v_max3_f32 v4, v4, v86, v87
	v_max3_f32 v4, v4, v88, v89
	v_max3_f32 v4, v4, v90, v91
	v_max3_f32 v4, v4, v92, v93
	v_max3_f32 v4, v4, v94, v95
	v_mov_b32_e32 v5, v4
	s_nop 1
	v_permlane32_swap_b32_e32 v5, v4
	s_nop 1
	s_waitcnt lgkmcnt(0)
	v_max_f32_e32 v4, v4, v5
	v_add_f32_e32 v5, 0x41000000, v205
	v_cmp_gt_f32_e32 vcc, v4, v5
	s_cbranch_vccz .LBB0_210
	v_max_f32_e32 v5, v205, v4
	v_sub_f32_e32 v4, v205, v5
	v_exp_f32_e32 v4, v4
	v_mov_b32_e32 v205, v5
	v_mul_f32_e32 v208, v208, v4
	v_pk_mul_f32 v[46:47], v[46:47], v[4:5] op_sel_hi:[1,0]
	v_pk_mul_f32 v[44:45], v[44:45], v[4:5] op_sel_hi:[1,0]
	v_pk_mul_f32 v[42:43], v[42:43], v[4:5] op_sel_hi:[1,0]
	v_pk_mul_f32 v[40:41], v[40:41], v[4:5] op_sel_hi:[1,0]
	v_pk_mul_f32 v[38:39], v[38:39], v[4:5] op_sel_hi:[1,0]
	v_pk_mul_f32 v[36:37], v[36:37], v[4:5] op_sel_hi:[1,0]
	v_pk_mul_f32 v[34:35], v[34:35], v[4:5] op_sel_hi:[1,0]
	v_pk_mul_f32 v[32:33], v[32:33], v[4:5] op_sel_hi:[1,0]
	v_pk_mul_f32 v[30:31], v[30:31], v[4:5] op_sel_hi:[1,0]
	v_pk_mul_f32 v[28:29], v[28:29], v[4:5] op_sel_hi:[1,0]
	v_pk_mul_f32 v[26:27], v[26:27], v[4:5] op_sel_hi:[1,0]
	v_pk_mul_f32 v[24:25], v[24:25], v[4:5] op_sel_hi:[1,0]
	v_pk_mul_f32 v[22:23], v[22:23], v[4:5] op_sel_hi:[1,0]
	v_pk_mul_f32 v[20:21], v[20:21], v[4:5] op_sel_hi:[1,0]
	v_pk_mul_f32 v[18:19], v[18:19], v[4:5] op_sel_hi:[1,0]
	v_pk_mul_f32 v[16:17], v[16:17], v[4:5] op_sel_hi:[1,0]
.LBB0_210:
	v_sub_f32_e32 v4, v96, v1
	v_exp_f32_e32 v4, v4
	v_sub_f32_e32 v6, v97, v1
	v_exp_f32_e32 v6, v6
	v_sub_f32_e32 v7, v98, v1
	v_exp_f32_e32 v7, v7
	v_sub_f32_e32 v8, v99, v1
	v_exp_f32_e32 v8, v8
	v_add_f32_e32 v5, v6, v4
	v_add_f32_e32 v5, v7, v5
	v_add_f32_e32 v5, v8, v5
	v_cvt_pk_bf16_f32 v97, v7, v8
	v_sub_f32_e32 v8, v80, v205
	v_exp_f32_e32 v224, v8
	v_sub_f32_e32 v8, v81, v205
	v_exp_f32_e32 v226, v8
	v_sub_f32_e32 v8, v82, v205
	v_exp_f32_e32 v227, v8
	v_sub_f32_e32 v8, v83, v205
	v_exp_f32_e32 v228, v8
	v_sub_f32_e32 v8, v84, v205
	v_exp_f32_e32 v229, v8
	v_sub_f32_e32 v8, v85, v205
	v_exp_f32_e32 v230, v8
	v_sub_f32_e32 v8, v86, v205
	v_exp_f32_e32 v231, v8
	v_sub_f32_e32 v8, v87, v205
	v_exp_f32_e32 v232, v8
	v_sub_f32_e32 v8, v88, v205
	v_exp_f32_e32 v233, v8
	v_sub_f32_e32 v8, v89, v205
	v_add3_u32 v219, v219, v209, v160
	v_exp_f32_e32 v234, v8
	v_sub_f32_e32 v8, v90, v205
	v_lshl_add_u32 v84, v211, 1, v219
	v_lshl_add_u32 v88, v210, 1, v219
	v_exp_f32_e32 v235, v8
	v_sub_f32_e32 v8, v91, v205
	ds_read_b64 v[238:239], v84 offset:8192
	ds_read_b64 v[242:243], v84 offset:12288
	ds_read_b64 v[240:241], v88 offset:8192
	ds_read_b64 v[244:245], v88 offset:12288
	v_exp_f32_e32 v236, v8
	v_sub_f32_e32 v8, v92, v205
	v_sub_f32_e32 v9, v100, v1
	v_sub_f32_e32 v96, v103, v1
	v_exp_f32_e32 v237, v8
	v_sub_f32_e32 v8, v93, v205
	v_exp_f32_e32 v9, v9
	v_sub_f32_e32 v10, v101, v1
	v_exp_f32_e32 v99, v96
	v_sub_f32_e32 v96, v104, v1
	v_exp_f32_e32 v222, v8
	v_sub_f32_e32 v8, v94, v205
	v_exp_f32_e32 v10, v10
	v_sub_f32_e32 v11, v102, v1
	v_exp_f32_e32 v100, v96
	v_sub_f32_e32 v96, v105, v1
	v_exp_f32_e32 v223, v8
	v_sub_f32_e32 v8, v95, v205
	s_waitcnt lgkmcnt(0)
	v_exp_f32_e32 v11, v11
	v_exp_f32_e32 v101, v96
	v_sub_f32_e32 v96, v106, v1
	v_exp_f32_e32 v102, v96
	v_sub_f32_e32 v96, v107, v1
	v_add_f32_e32 v5, v9, v5
	v_exp_f32_e32 v103, v96
	v_sub_f32_e32 v96, v108, v1
	v_add_f32_e32 v5, v10, v5
	v_exp_f32_e32 v104, v96
	v_sub_f32_e32 v96, v109, v1
	v_cvt_pk_bf16_f32 v80, v224, v226
	v_cvt_pk_bf16_f32 v81, v227, v228
	v_cvt_pk_bf16_f32 v82, v229, v230
	v_cvt_pk_bf16_f32 v83, v231, v232
	v_add_f32_e32 v5, v11, v5
	v_exp_f32_e32 v105, v96
	v_sub_f32_e32 v96, v110, v1
	v_mfma_f32_32x32x16_bf16 v[32:47], v[238:241], v[80:83], v[32:47]
	v_lshl_add_u32 v84, v206, 1, v219
	v_add_f32_e32 v5, v99, v5
	v_exp_f32_e32 v106, v96
	v_sub_f32_e32 v96, v111, v1
	ds_read2st64_b64 v[84:87], v84 offset0:16 offset1:24
	v_add_f32_e32 v5, v100, v5
	v_exp_f32_e32 v107, v96
	v_mfma_f32_32x32x16_bf16 v[16:31], v[242:245], v[80:83], v[16:31]
	v_lshl_add_u32 v80, v207, 1, v219
	ds_read2st64_b64 v[80:83], v80 offset0:16 offset1:24
	v_cvt_pk_bf16_f32 v96, v4, v6
	v_cvt_pk_bf16_f32 v98, v9, v10
	v_cvt_pk_bf16_f32 v99, v11, v99
	v_add_f32_e32 v5, v101, v5
	v_add_f32_e32 v5, v102, v5
	v_mfma_f32_32x32x16_bf16 v[64:79], v[238:241], v[96:99], v[64:79]
	v_add_f32_e32 v5, v103, v5
	v_add_f32_e32 v5, v104, v5
	v_add_f32_e32 v5, v105, v5
	v_add_f32_e32 v5, v106, v5
	v_add_f32_e32 v5, v107, v5
	v_add_f32_e32 v3, v3, v5
	v_cvt_pk_bf16_f32 v4, v100, v101
	v_mfma_f32_32x32x16_bf16 v[48:63], v[242:245], v[96:99], v[48:63]
	s_waitcnt lgkmcnt(0)
	v_mov_b32_e32 v88, v80
	v_mov_b32_e32 v89, v81
	v_mov_b32_e32 v90, v84
	v_mov_b32_e32 v91, v85
	v_mov_b32_e32 v84, v82
	v_mov_b32_e32 v85, v83
	v_cvt_pk_bf16_f32 v5, v102, v103
	v_cvt_pk_bf16_f32 v6, v104, v105
	v_cvt_pk_bf16_f32 v7, v106, v107
	v_exp_f32_e32 v225, v8
	v_cvt_pk_bf16_f32 v8, v233, v234
	v_mfma_f32_32x32x16_bf16 v[64:79], v[88:91], v[4:7], v[64:79]
	v_cvt_pk_bf16_f32 v9, v235, v236
	v_cvt_pk_bf16_f32 v10, v237, v222
	v_cvt_pk_bf16_f32 v11, v223, v225
	v_mfma_f32_32x32x16_bf16 v[48:63], v[84:87], v[4:7], v[48:63]
	ds_read_b128 v[4:7], v220 offset:4096
	v_mfma_f32_32x32x16_bf16 v[32:47], v[88:91], v[8:11], v[32:47]
	v_mfma_f32_32x32x16_bf16 v[16:31], v[84:87], v[8:11], v[16:31]
	s_waitcnt lgkmcnt(0)
	v_mfma_f32_32x32x16_bf16 v[96:111], v[4:7], v[152:155], 0
	v_mfma_f32_32x32x16_bf16 v[80:95], v[4:7], v[156:159], 0
	ds_read_b128 v[4:7], v14 offset:4096
	s_waitcnt lgkmcnt(0)
	v_mfma_f32_32x32x16_bf16 v[96:111], v[4:7], v[140:143], v[96:111]
	v_mfma_f32_32x32x16_bf16 v[80:95], v[4:7], v[148:151], v[80:95]
	ds_read_b128 v[4:7], v221 offset:4096
	s_waitcnt lgkmcnt(0)
	v_mfma_f32_32x32x16_bf16 v[96:111], v[4:7], v[136:139], v[96:111]
	v_mfma_f32_32x32x16_bf16 v[80:95], v[4:7], v[144:147], v[80:95]
	ds_read_b128 v[4:7], v13 offset:4096
	s_waitcnt lgkmcnt(0)
	v_mfma_f32_32x32x16_bf16 v[96:111], v[4:7], v[124:127], v[96:111]
	v_mfma_f32_32x32x16_bf16 v[80:95], v[4:7], v[132:135], v[80:95]
	ds_read_b128 v[4:7], v15 offset:18432
	s_waitcnt lgkmcnt(0)
	v_mfma_f32_32x32x16_bf16 v[96:111], v[4:7], v[120:123], v[96:111]
	v_mfma_f32_32x32x16_bf16 v[80:95], v[4:7], v[128:131], v[80:95]
	ds_read_b128 v[4:7], v12 offset:18432
	s_waitcnt lgkmcnt(0)
	v_mfma_f32_32x32x16_bf16 v[96:111], v[4:7], v[112:115], v[96:111]
	v_mfma_f32_32x32x16_bf16 v[80:95], v[4:7], v[116:119], v[80:95]
	s_nop 10
	v_max_f32_e32 v4, v96, v97
	v_max3_f32 v4, v4, v98, v99
	v_max3_f32 v4, v4, v100, v101
	v_max3_f32 v4, v4, v102, v103
	v_max3_f32 v4, v4, v104, v105
	v_max3_f32 v4, v4, v106, v107
	v_max3_f32 v4, v4, v108, v109
	v_max3_f32 v4, v4, v110, v111
	v_mov_b32_e32 v5, v4
	s_nop 1
	v_permlane32_swap_b32_e32 v5, v4
	s_nop 1
	s_waitcnt lgkmcnt(0)
	v_max_f32_e32 v4, v4, v5
	v_add_f32_e32 v5, 0x41000000, v1
	v_cmp_gt_f32_e32 vcc, v4, v5
	s_cbranch_vccz .LBB0_212
	v_max_f32_e32 v5, v1, v4
	v_sub_f32_e32 v1, v1, v5
	v_exp_f32_e32 v4, v1
	v_mov_b32_e32 v1, v5
	v_mul_f32_e32 v3, v3, v4
	v_pk_mul_f32 v[78:79], v[78:79], v[4:5] op_sel_hi:[1,0]
	v_pk_mul_f32 v[76:77], v[76:77], v[4:5] op_sel_hi:[1,0]
	v_pk_mul_f32 v[74:75], v[74:75], v[4:5] op_sel_hi:[1,0]
	v_pk_mul_f32 v[72:73], v[72:73], v[4:5] op_sel_hi:[1,0]
	v_pk_mul_f32 v[70:71], v[70:71], v[4:5] op_sel_hi:[1,0]
	v_pk_mul_f32 v[68:69], v[68:69], v[4:5] op_sel_hi:[1,0]
	v_pk_mul_f32 v[66:67], v[66:67], v[4:5] op_sel_hi:[1,0]
	v_pk_mul_f32 v[64:65], v[64:65], v[4:5] op_sel_hi:[1,0]
	v_pk_mul_f32 v[62:63], v[62:63], v[4:5] op_sel_hi:[1,0]
	v_pk_mul_f32 v[60:61], v[60:61], v[4:5] op_sel_hi:[1,0]
	v_pk_mul_f32 v[58:59], v[58:59], v[4:5] op_sel_hi:[1,0]
	v_pk_mul_f32 v[56:57], v[56:57], v[4:5] op_sel_hi:[1,0]
	v_pk_mul_f32 v[54:55], v[54:55], v[4:5] op_sel_hi:[1,0]
	v_pk_mul_f32 v[52:53], v[52:53], v[4:5] op_sel_hi:[1,0]
	v_pk_mul_f32 v[50:51], v[50:51], v[4:5] op_sel_hi:[1,0]
	v_pk_mul_f32 v[48:49], v[48:49], v[4:5] op_sel_hi:[1,0]
.LBB0_212:
	v_add_f32_e32 v4, v226, v224
	v_add_f32_e32 v4, v227, v4
	v_add_f32_e32 v4, v228, v4
	v_max_f32_e32 v5, v80, v81
	v_add_f32_e32 v4, v229, v4
	v_max3_f32 v5, v5, v82, v83
	v_add_f32_e32 v4, v230, v4
	v_max3_f32 v5, v5, v84, v85
	v_add_f32_e32 v4, v231, v4
	v_max3_f32 v5, v5, v86, v87
	v_add_f32_e32 v4, v232, v4
	v_max3_f32 v5, v5, v88, v89
	v_add_f32_e32 v4, v233, v4
	v_max3_f32 v5, v5, v90, v91
	v_add_f32_e32 v4, v234, v4
	v_max3_f32 v5, v5, v92, v93
	v_add_f32_e32 v4, v235, v4
	v_max3_f32 v5, v5, v94, v95
	v_add_f32_e32 v4, v236, v4
	v_mov_b32_e32 v6, v5
	s_nop 1
	v_permlane32_swap_b32_e32 v6, v5
	s_nop 1
	v_add_f32_e32 v4, v237, v4
	v_add_f32_e32 v4, v222, v4
	v_add_f32_e32 v4, v223, v4
	v_add_f32_e32 v4, v225, v4
	v_add_f32_e32 v8, v208, v4
	s_waitcnt lgkmcnt(0)
	v_max_f32_e32 v4, v5, v6
	v_add_f32_e32 v5, 0x41000000, v205
	v_cmp_gt_f32_e32 vcc, v4, v5
	s_cbranch_vccz .LBB0_203
	v_max_f32_e32 v5, v205, v4
	v_sub_f32_e32 v4, v205, v5
	v_exp_f32_e32 v4, v4
	v_mov_b32_e32 v205, v5
	v_mul_f32_e32 v8, v8, v4
	v_pk_mul_f32 v[46:47], v[46:47], v[4:5] op_sel_hi:[1,0]
	v_pk_mul_f32 v[44:45], v[44:45], v[4:5] op_sel_hi:[1,0]
	v_pk_mul_f32 v[42:43], v[42:43], v[4:5] op_sel_hi:[1,0]
	v_pk_mul_f32 v[40:41], v[40:41], v[4:5] op_sel_hi:[1,0]
	v_pk_mul_f32 v[38:39], v[38:39], v[4:5] op_sel_hi:[1,0]
	v_pk_mul_f32 v[36:37], v[36:37], v[4:5] op_sel_hi:[1,0]
	v_pk_mul_f32 v[34:35], v[34:35], v[4:5] op_sel_hi:[1,0]
	v_pk_mul_f32 v[32:33], v[32:33], v[4:5] op_sel_hi:[1,0]
	v_pk_mul_f32 v[30:31], v[30:31], v[4:5] op_sel_hi:[1,0]
	v_pk_mul_f32 v[28:29], v[28:29], v[4:5] op_sel_hi:[1,0]
	v_pk_mul_f32 v[26:27], v[26:27], v[4:5] op_sel_hi:[1,0]
	v_pk_mul_f32 v[24:25], v[24:25], v[4:5] op_sel_hi:[1,0]
	v_pk_mul_f32 v[22:23], v[22:23], v[4:5] op_sel_hi:[1,0]
	v_pk_mul_f32 v[20:21], v[20:21], v[4:5] op_sel_hi:[1,0]
	v_pk_mul_f32 v[18:19], v[18:19], v[4:5] op_sel_hi:[1,0]
	v_pk_mul_f32 v[16:17], v[16:17], v[4:5] op_sel_hi:[1,0]
	s_branch .LBB0_203
.LBB0_214:
	s_waitcnt vmcnt(0) lgkmcnt(0)
	s_barrier
	v_lshlrev_b32_e32 v8, 1, v209
	v_lshl_add_u32 v14, v218, 1, v8
	ds_read_b128 v[4:7], v14
	v_lshl_add_u32 v15, v217, 1, v8
	v_lshl_add_u32 v162, v216, 1, v8
	v_lshl_add_u32 v163, v215, 1, v8
	v_sub_u32_e32 v215, v8, v209
	v_lshl_add_u32 v164, v214, 1, v215
	v_lshl_add_u32 v13, v213, 1, v215
	s_waitcnt lgkmcnt(0)
	v_mfma_f32_32x32x16_bf16 v[96:111], v[4:7], v[152:155], 0
	v_mfma_f32_32x32x16_bf16 v[80:95], v[4:7], v[156:159], 0
	ds_read_b128 v[4:7], v15
	s_waitcnt lgkmcnt(0)
	v_mfma_f32_32x32x16_bf16 v[96:111], v[4:7], v[140:143], v[96:111]
	v_mfma_f32_32x32x16_bf16 v[80:95], v[4:7], v[148:151], v[80:95]
	ds_read_b128 v[4:7], v162
	s_waitcnt lgkmcnt(0)
	v_mfma_f32_32x32x16_bf16 v[96:111], v[4:7], v[136:139], v[96:111]
	v_mfma_f32_32x32x16_bf16 v[80:95], v[4:7], v[144:147], v[80:95]
	ds_read_b128 v[4:7], v163
	s_waitcnt lgkmcnt(0)
	v_mfma_f32_32x32x16_bf16 v[96:111], v[4:7], v[124:127], v[96:111]
	v_mfma_f32_32x32x16_bf16 v[80:95], v[4:7], v[132:135], v[80:95]
	ds_read_b128 v[4:7], v164 offset:16384
	s_waitcnt lgkmcnt(0)
	v_mfma_f32_32x32x16_bf16 v[96:111], v[4:7], v[120:123], v[96:111]
	v_mfma_f32_32x32x16_bf16 v[80:95], v[4:7], v[128:131], v[80:95]
	ds_read_b128 v[4:7], v13 offset:16384
	s_waitcnt lgkmcnt(0)
	v_mfma_f32_32x32x16_bf16 v[96:111], v[4:7], v[112:115], v[96:111]
	v_mfma_f32_32x32x16_bf16 v[80:95], v[4:7], v[116:119], v[80:95]
	s_nop 10
	v_max_f32_e32 v4, v96, v97
	v_max3_f32 v4, v4, v98, v99
	v_max3_f32 v4, v4, v100, v101
	v_max3_f32 v4, v4, v102, v103
	v_max3_f32 v4, v4, v104, v105
	v_max3_f32 v4, v4, v106, v107
	v_max3_f32 v4, v4, v108, v109
	v_max3_f32 v4, v4, v110, v111
	v_mov_b32_e32 v5, v4
	s_nop 1
	v_permlane32_swap_b32_e32 v5, v4
	s_nop 1
	s_waitcnt lgkmcnt(0)
	v_max_f32_e32 v4, v4, v5
	v_add_f32_e32 v5, 0x41000000, v1
	v_cmp_gt_f32_e32 vcc, v4, v5
	s_cbranch_vccz .LBB0_216
	v_max_f32_e32 v5, v1, v4
	v_sub_f32_e32 v1, v1, v5
	v_exp_f32_e32 v4, v1
	v_mov_b32_e32 v1, v5
	v_mul_f32_e32 v3, v3, v4
	v_pk_mul_f32 v[78:79], v[78:79], v[4:5] op_sel_hi:[1,0]
	v_pk_mul_f32 v[76:77], v[76:77], v[4:5] op_sel_hi:[1,0]
	v_pk_mul_f32 v[74:75], v[74:75], v[4:5] op_sel_hi:[1,0]
	v_pk_mul_f32 v[72:73], v[72:73], v[4:5] op_sel_hi:[1,0]
	v_pk_mul_f32 v[70:71], v[70:71], v[4:5] op_sel_hi:[1,0]
	v_pk_mul_f32 v[68:69], v[68:69], v[4:5] op_sel_hi:[1,0]
	v_pk_mul_f32 v[66:67], v[66:67], v[4:5] op_sel_hi:[1,0]
	v_pk_mul_f32 v[64:65], v[64:65], v[4:5] op_sel_hi:[1,0]
	v_pk_mul_f32 v[62:63], v[62:63], v[4:5] op_sel_hi:[1,0]
	v_pk_mul_f32 v[60:61], v[60:61], v[4:5] op_sel_hi:[1,0]
	v_pk_mul_f32 v[58:59], v[58:59], v[4:5] op_sel_hi:[1,0]
	v_pk_mul_f32 v[56:57], v[56:57], v[4:5] op_sel_hi:[1,0]
	v_pk_mul_f32 v[54:55], v[54:55], v[4:5] op_sel_hi:[1,0]
	v_pk_mul_f32 v[52:53], v[52:53], v[4:5] op_sel_hi:[1,0]
	v_pk_mul_f32 v[50:51], v[50:51], v[4:5] op_sel_hi:[1,0]
	v_pk_mul_f32 v[48:49], v[48:49], v[4:5] op_sel_hi:[1,0]
.LBB0_216:
	v_max_f32_e32 v4, v80, v81
	v_max3_f32 v4, v4, v82, v83
	v_max3_f32 v4, v4, v84, v85
	v_max3_f32 v4, v4, v86, v87
	v_max3_f32 v4, v4, v88, v89
	v_max3_f32 v4, v4, v90, v91
	v_max3_f32 v4, v4, v92, v93
	v_max3_f32 v4, v4, v94, v95
	v_mov_b32_e32 v5, v4
	s_nop 1
	v_permlane32_swap_b32_e32 v5, v4
	s_nop 1
	s_waitcnt lgkmcnt(0)
	v_max_f32_e32 v4, v4, v5
	v_add_f32_e32 v5, 0x41000000, v205
	v_cmp_gt_f32_e32 vcc, v4, v5
	s_cbranch_vccz .LBB0_218
	v_max_f32_e32 v5, v205, v4
	v_sub_f32_e32 v4, v205, v5
	v_exp_f32_e32 v4, v4
	v_mov_b32_e32 v205, v5
	v_mul_f32_e32 v208, v208, v4
	v_pk_mul_f32 v[46:47], v[46:47], v[4:5] op_sel_hi:[1,0]
	v_pk_mul_f32 v[44:45], v[44:45], v[4:5] op_sel_hi:[1,0]
	v_pk_mul_f32 v[42:43], v[42:43], v[4:5] op_sel_hi:[1,0]
	v_pk_mul_f32 v[40:41], v[40:41], v[4:5] op_sel_hi:[1,0]
	v_pk_mul_f32 v[38:39], v[38:39], v[4:5] op_sel_hi:[1,0]
	v_pk_mul_f32 v[36:37], v[36:37], v[4:5] op_sel_hi:[1,0]
	v_pk_mul_f32 v[34:35], v[34:35], v[4:5] op_sel_hi:[1,0]
	v_pk_mul_f32 v[32:33], v[32:33], v[4:5] op_sel_hi:[1,0]
	v_pk_mul_f32 v[30:31], v[30:31], v[4:5] op_sel_hi:[1,0]
	v_pk_mul_f32 v[28:29], v[28:29], v[4:5] op_sel_hi:[1,0]
	v_pk_mul_f32 v[26:27], v[26:27], v[4:5] op_sel_hi:[1,0]
	v_pk_mul_f32 v[24:25], v[24:25], v[4:5] op_sel_hi:[1,0]
	v_pk_mul_f32 v[22:23], v[22:23], v[4:5] op_sel_hi:[1,0]
	v_pk_mul_f32 v[20:21], v[20:21], v[4:5] op_sel_hi:[1,0]
	v_pk_mul_f32 v[18:19], v[18:19], v[4:5] op_sel_hi:[1,0]
	v_pk_mul_f32 v[16:17], v[16:17], v[4:5] op_sel_hi:[1,0]
.LBB0_218:
	v_sub_f32_e32 v4, v96, v1
	v_exp_f32_e32 v4, v4
	v_sub_f32_e32 v6, v97, v1
	v_exp_f32_e32 v6, v6
	v_sub_f32_e32 v7, v98, v1
	v_exp_f32_e32 v7, v7
	v_sub_f32_e32 v8, v99, v1
	v_exp_f32_e32 v8, v8
	v_sub_f32_e32 v9, v100, v1
	v_exp_f32_e32 v9, v9
	v_sub_f32_e32 v10, v101, v1
	v_add_f32_e32 v5, v6, v4
	v_exp_f32_e32 v10, v10
	v_sub_f32_e32 v11, v102, v1
	v_add_f32_e32 v5, v7, v5
	v_exp_f32_e32 v11, v11
	v_sub_f32_e32 v12, v103, v1
	v_add_f32_e32 v5, v8, v5
	v_exp_f32_e32 v99, v12
	v_sub_f32_e32 v12, v104, v1
	v_add_f32_e32 v5, v9, v5
	v_exp_f32_e32 v100, v12
	v_sub_f32_e32 v12, v105, v1
	v_add_f32_e32 v5, v10, v5
	v_exp_f32_e32 v101, v12
	v_sub_f32_e32 v12, v106, v1
	v_add_f32_e32 v5, v11, v5
	v_exp_f32_e32 v102, v12
	v_sub_f32_e32 v12, v107, v1
	v_add_f32_e32 v5, v99, v5
	v_exp_f32_e32 v103, v12
	v_sub_f32_e32 v12, v108, v1
	v_add_f32_e32 v5, v100, v5
	v_exp_f32_e32 v104, v12
	v_sub_f32_e32 v12, v109, v1
	v_add_f32_e32 v5, v101, v5
	v_exp_f32_e32 v105, v12
	v_sub_f32_e32 v12, v110, v1
	v_add_f32_e32 v5, v102, v5
	v_exp_f32_e32 v106, v12
	v_sub_f32_e32 v12, v111, v1
	v_add_f32_e32 v5, v103, v5
	v_exp_f32_e32 v107, v12
	v_add_f32_e32 v5, v104, v5
	v_add_f32_e32 v5, v105, v5
	v_add_f32_e32 v5, v106, v5
	v_add_f32_e32 v5, v107, v5
	v_add_f32_e32 v12, v3, v5
	v_sub_f32_e32 v3, v80, v205
	v_exp_f32_e32 v167, v3
	v_sub_f32_e32 v3, v81, v205
	v_exp_f32_e32 v213, v3
	v_sub_f32_e32 v3, v82, v205
	v_exp_f32_e32 v214, v3
	v_sub_f32_e32 v3, v83, v205
	v_exp_f32_e32 v216, v3
	v_sub_f32_e32 v3, v84, v205
	v_exp_f32_e32 v217, v3
	v_sub_f32_e32 v3, v85, v205
	v_exp_f32_e32 v218, v3
	v_sub_f32_e32 v3, v86, v205
	v_exp_f32_e32 v219, v3
	v_sub_f32_e32 v3, v87, v205
	v_exp_f32_e32 v220, v3
	v_sub_f32_e32 v3, v88, v205
	v_exp_f32_e32 v221, v3
	v_sub_f32_e32 v3, v89, v205
	v_exp_f32_e32 v222, v3
	v_sub_f32_e32 v3, v90, v205
	v_exp_f32_e32 v223, v3
	v_sub_f32_e32 v3, v91, v205
	v_exp_f32_e32 v224, v3
	v_sub_f32_e32 v3, v92, v205
	v_exp_f32_e32 v225, v3
	v_sub_f32_e32 v3, v93, v205
	v_exp_f32_e32 v165, v3
	v_sub_f32_e32 v3, v94, v205
	v_exp_f32_e32 v166, v3
	v_sub_f32_e32 v3, v95, v205
	v_exp_f32_e32 v212, v3
	v_add3_u32 v3, v215, v209, v160
	v_lshl_add_u32 v84, v211, 1, v3
	v_lshl_add_u32 v88, v210, 1, v3
	ds_read_b64 v[238:239], v84 offset:8192
	ds_read_b64 v[242:243], v84 offset:12288
	ds_read_b64 v[240:241], v88 offset:8192
	ds_read_b64 v[244:245], v88 offset:12288
	v_cvt_pk_bf16_f32 v80, v167, v213
	v_cvt_pk_bf16_f32 v81, v214, v216
	v_cvt_pk_bf16_f32 v82, v217, v218
	s_waitcnt lgkmcnt(0)
	v_cvt_pk_bf16_f32 v83, v219, v220
	v_lshl_add_u32 v84, v206, 1, v3
	ds_read2st64_b64 v[84:87], v84 offset0:16 offset1:24
	v_mfma_f32_32x32x16_bf16 v[32:47], v[238:241], v[80:83], v[32:47]
	v_cvt_pk_bf16_f32 v96, v4, v6
	v_cvt_pk_bf16_f32 v97, v7, v8
	v_cvt_pk_bf16_f32 v98, v9, v10
	v_cvt_pk_bf16_f32 v99, v11, v99
	v_cvt_pk_bf16_f32 v4, v100, v101
	v_cvt_pk_bf16_f32 v5, v102, v103
	v_cvt_pk_bf16_f32 v6, v104, v105
	v_mfma_f32_32x32x16_bf16 v[16:31], v[242:245], v[80:83], v[16:31]
	v_lshl_add_u32 v80, v207, 1, v3
	ds_read2st64_b64 v[80:83], v80 offset0:16 offset1:24
	v_cvt_pk_bf16_f32 v7, v106, v107
	v_cvt_pk_bf16_f32 v8, v221, v222
	v_cvt_pk_bf16_f32 v9, v223, v224
	v_cvt_pk_bf16_f32 v10, v225, v165
	v_cvt_pk_bf16_f32 v11, v166, v212
	v_mfma_f32_32x32x16_bf16 v[64:79], v[238:241], v[96:99], v[64:79]
	v_mfma_f32_32x32x16_bf16 v[48:63], v[242:245], v[96:99], v[48:63]
	s_waitcnt lgkmcnt(0)
	v_mov_b32_e32 v88, v80
	v_mov_b32_e32 v89, v81
	v_mov_b32_e32 v90, v84
	v_mov_b32_e32 v91, v85
	v_mov_b32_e32 v84, v82
	v_mov_b32_e32 v85, v83
	v_mfma_f32_32x32x16_bf16 v[64:79], v[88:91], v[4:7], v[64:79]
	s_nop 0
	v_mfma_f32_32x32x16_bf16 v[48:63], v[84:87], v[4:7], v[48:63]
	ds_read_b128 v[4:7], v14 offset:4096
	v_mfma_f32_32x32x16_bf16 v[32:47], v[88:91], v[8:11], v[32:47]
	v_mfma_f32_32x32x16_bf16 v[16:31], v[84:87], v[8:11], v[16:31]
	s_waitcnt lgkmcnt(0)
	v_mfma_f32_32x32x16_bf16 v[96:111], v[4:7], v[152:155], 0
	v_mfma_f32_32x32x16_bf16 v[80:95], v[4:7], v[156:159], 0
	ds_read_b128 v[4:7], v15 offset:4096
	s_waitcnt lgkmcnt(0)
	v_mfma_f32_32x32x16_bf16 v[96:111], v[4:7], v[140:143], v[96:111]
	v_mfma_f32_32x32x16_bf16 v[80:95], v[4:7], v[148:151], v[80:95]
	ds_read_b128 v[4:7], v162 offset:4096
	s_waitcnt lgkmcnt(0)
	v_mfma_f32_32x32x16_bf16 v[96:111], v[4:7], v[136:139], v[96:111]
	v_mfma_f32_32x32x16_bf16 v[80:95], v[4:7], v[144:147], v[80:95]
	ds_read_b128 v[4:7], v163 offset:4096
	s_waitcnt lgkmcnt(0)
	v_mfma_f32_32x32x16_bf16 v[96:111], v[4:7], v[124:127], v[96:111]
	v_mfma_f32_32x32x16_bf16 v[80:95], v[4:7], v[132:135], v[80:95]
	ds_read_b128 v[4:7], v164 offset:18432
	s_waitcnt lgkmcnt(0)
	v_mfma_f32_32x32x16_bf16 v[96:111], v[4:7], v[120:123], v[96:111]
	v_mfma_f32_32x32x16_bf16 v[80:95], v[4:7], v[128:131], v[80:95]
	ds_read_b128 v[4:7], v13 offset:18432
	s_waitcnt lgkmcnt(0)
	v_mfma_f32_32x32x16_bf16 v[96:111], v[4:7], v[112:115], v[96:111]
	v_mfma_f32_32x32x16_bf16 v[80:95], v[4:7], v[116:119], v[80:95]
	s_nop 10
	v_max_f32_e32 v4, v96, v97
	v_max3_f32 v4, v4, v98, v99
	v_max3_f32 v4, v4, v100, v101
	v_max3_f32 v4, v4, v102, v103
	v_max3_f32 v4, v4, v104, v105
	v_max3_f32 v4, v4, v106, v107
	v_max3_f32 v4, v4, v108, v109
	v_max3_f32 v4, v4, v110, v111
	v_mov_b32_e32 v5, v4
	s_nop 1
	v_permlane32_swap_b32_e32 v5, v4
	s_nop 1
	s_waitcnt lgkmcnt(0)
	v_max_f32_e32 v4, v4, v5
	v_add_f32_e32 v5, 0x41000000, v1
	v_cmp_gt_f32_e32 vcc, v4, v5
	s_cbranch_vccz .LBB0_220
	v_max_f32_e32 v5, v1, v4
	v_sub_f32_e32 v1, v1, v5
	v_exp_f32_e32 v4, v1
	v_mov_b32_e32 v1, v5
	v_mul_f32_e32 v12, v12, v4
	v_pk_mul_f32 v[78:79], v[78:79], v[4:5] op_sel_hi:[1,0]
	v_pk_mul_f32 v[76:77], v[76:77], v[4:5] op_sel_hi:[1,0]
	v_pk_mul_f32 v[74:75], v[74:75], v[4:5] op_sel_hi:[1,0]
	v_pk_mul_f32 v[72:73], v[72:73], v[4:5] op_sel_hi:[1,0]
	v_pk_mul_f32 v[70:71], v[70:71], v[4:5] op_sel_hi:[1,0]
	v_pk_mul_f32 v[68:69], v[68:69], v[4:5] op_sel_hi:[1,0]
	v_pk_mul_f32 v[66:67], v[66:67], v[4:5] op_sel_hi:[1,0]
	v_pk_mul_f32 v[64:65], v[64:65], v[4:5] op_sel_hi:[1,0]
	v_pk_mul_f32 v[62:63], v[62:63], v[4:5] op_sel_hi:[1,0]
	v_pk_mul_f32 v[60:61], v[60:61], v[4:5] op_sel_hi:[1,0]
	v_pk_mul_f32 v[58:59], v[58:59], v[4:5] op_sel_hi:[1,0]
	v_pk_mul_f32 v[56:57], v[56:57], v[4:5] op_sel_hi:[1,0]
	v_pk_mul_f32 v[54:55], v[54:55], v[4:5] op_sel_hi:[1,0]
	v_pk_mul_f32 v[52:53], v[52:53], v[4:5] op_sel_hi:[1,0]
	v_pk_mul_f32 v[50:51], v[50:51], v[4:5] op_sel_hi:[1,0]
	v_pk_mul_f32 v[48:49], v[48:49], v[4:5] op_sel_hi:[1,0]
.LBB0_220:
	v_add_f32_e32 v4, v213, v167
	v_add_f32_e32 v4, v214, v4
	v_add_f32_e32 v4, v216, v4
	v_max_f32_e32 v5, v80, v81
	v_add_f32_e32 v4, v217, v4
	v_max3_f32 v5, v5, v82, v83
	v_add_f32_e32 v4, v218, v4
	v_max3_f32 v5, v5, v84, v85
	v_add_f32_e32 v4, v219, v4
	v_max3_f32 v5, v5, v86, v87
	v_add_f32_e32 v4, v220, v4
	v_max3_f32 v5, v5, v88, v89
	v_add_f32_e32 v4, v221, v4
	v_max3_f32 v5, v5, v90, v91
	v_add_f32_e32 v4, v222, v4
	v_max3_f32 v5, v5, v92, v93
	v_add_f32_e32 v4, v223, v4
	v_max3_f32 v5, v5, v94, v95
	v_add_f32_e32 v4, v224, v4
	v_mov_b32_e32 v6, v5
	s_nop 1
	v_permlane32_swap_b32_e32 v6, v5
	s_nop 1
	v_add_f32_e32 v4, v225, v4
	v_add_f32_e32 v4, v165, v4
	v_add_f32_e32 v4, v166, v4
	v_add_f32_e32 v4, v212, v4
	v_add_f32_e32 v8, v208, v4
	s_waitcnt lgkmcnt(0)
	v_max_f32_e32 v4, v5, v6
	v_add_f32_e32 v5, 0x41000000, v205
	v_cmp_gt_f32_e32 vcc, v4, v5
	s_cbranch_vccz .LBB0_222
	v_max_f32_e32 v5, v205, v4
	v_sub_f32_e32 v4, v205, v5
	v_exp_f32_e32 v4, v4
	v_mov_b32_e32 v205, v5
	v_mul_f32_e32 v8, v8, v4
	v_pk_mul_f32 v[46:47], v[46:47], v[4:5] op_sel_hi:[1,0]
	v_pk_mul_f32 v[44:45], v[44:45], v[4:5] op_sel_hi:[1,0]
	v_pk_mul_f32 v[42:43], v[42:43], v[4:5] op_sel_hi:[1,0]
	v_pk_mul_f32 v[40:41], v[40:41], v[4:5] op_sel_hi:[1,0]
	v_pk_mul_f32 v[38:39], v[38:39], v[4:5] op_sel_hi:[1,0]
	v_pk_mul_f32 v[36:37], v[36:37], v[4:5] op_sel_hi:[1,0]
	v_pk_mul_f32 v[34:35], v[34:35], v[4:5] op_sel_hi:[1,0]
	v_pk_mul_f32 v[32:33], v[32:33], v[4:5] op_sel_hi:[1,0]
	v_pk_mul_f32 v[30:31], v[30:31], v[4:5] op_sel_hi:[1,0]
	v_pk_mul_f32 v[28:29], v[28:29], v[4:5] op_sel_hi:[1,0]
	v_pk_mul_f32 v[26:27], v[26:27], v[4:5] op_sel_hi:[1,0]
	v_pk_mul_f32 v[24:25], v[24:25], v[4:5] op_sel_hi:[1,0]
	v_pk_mul_f32 v[22:23], v[22:23], v[4:5] op_sel_hi:[1,0]
	v_pk_mul_f32 v[20:21], v[20:21], v[4:5] op_sel_hi:[1,0]
	v_pk_mul_f32 v[18:19], v[18:19], v[4:5] op_sel_hi:[1,0]
	v_pk_mul_f32 v[16:17], v[16:17], v[4:5] op_sel_hi:[1,0]

.LBB0_228:
	v_lshl_or_b32 v204, s41, 14, v165
	v_lshl_add_u32 v13, v203, 1, v204
	ds_read_b128 v[4:7], v13
	v_lshl_add_u32 v14, v202, 1, v204
	v_lshl_add_u32 v15, v201, 1, v204
	v_lshl_add_u32 v12, v167, 1, v204
	v_cmp_lt_i32_e32 vcc, v180, v182
	s_waitcnt lgkmcnt(0)
	v_mfma_f32_32x32x16_bf16 v[96:111], v[4:7], v[136:139], 0
	v_cndmask_b32_e32 v0, v179, v180, vcc
	v_lshlrev_b32_e32 v0, 2, v0
	v_mfma_f32_32x32x16_bf16 v[80:95], v[4:7], v[140:143], 0
	ds_read_b128 v[4:7], v14
	s_waitcnt lgkmcnt(0)
	v_mfma_f32_32x32x16_bf16 v[96:111], v[4:7], v[124:127], v[96:111]
	v_mfma_f32_32x32x16_bf16 v[80:95], v[4:7], v[132:135], v[80:95]
	ds_read_b128 v[4:7], v15
	s_waitcnt lgkmcnt(0)
	v_mfma_f32_32x32x16_bf16 v[96:111], v[4:7], v[120:123], v[96:111]
	v_mfma_f32_32x32x16_bf16 v[80:95], v[4:7], v[128:131], v[80:95]
	ds_read_b128 v[4:7], v12
	s_waitcnt lgkmcnt(0)
	v_mfma_f32_32x32x16_bf16 v[96:111], v[4:7], v[112:115], v[96:111]
	v_mfma_f32_32x32x16_bf16 v[80:95], v[4:7], v[116:119], v[80:95]
	s_nop 10
	v_max_f32_e32 v4, v96, v97
	v_max3_f32 v4, v4, v98, v99
	v_max3_f32 v4, v4, v100, v101
	v_max3_f32 v4, v4, v102, v103
	v_max3_f32 v4, v4, v104, v105
	v_max3_f32 v4, v4, v106, v107
	v_max3_f32 v4, v4, v108, v109
	v_max3_f32 v4, v4, v110, v111
	v_mov_b32_e32 v5, v4
	s_nop 1
	v_permlane32_swap_b32_e32 v5, v4
	s_nop 1
	s_waitcnt lgkmcnt(0)
	v_max_f32_e32 v4, v4, v5
	v_add_f32_e32 v5, 0x41000000, v1
	v_cmp_gt_f32_e32 vcc, v4, v5
	s_cbranch_vccz .LBB0_230
	v_max_f32_e32 v5, v1, v4
	v_sub_f32_e32 v1, v1, v5
	v_exp_f32_e32 v4, v1
	v_mov_b32_e32 v1, v5
	v_mul_f32_e32 v3, v3, v4
	v_pk_mul_f32 v[78:79], v[78:79], v[4:5] op_sel_hi:[1,0]
	v_pk_mul_f32 v[76:77], v[76:77], v[4:5] op_sel_hi:[1,0]
	v_pk_mul_f32 v[74:75], v[74:75], v[4:5] op_sel_hi:[1,0]
	v_pk_mul_f32 v[72:73], v[72:73], v[4:5] op_sel_hi:[1,0]
	v_pk_mul_f32 v[70:71], v[70:71], v[4:5] op_sel_hi:[1,0]
	v_pk_mul_f32 v[68:69], v[68:69], v[4:5] op_sel_hi:[1,0]
	v_pk_mul_f32 v[66:67], v[66:67], v[4:5] op_sel_hi:[1,0]
	v_pk_mul_f32 v[64:65], v[64:65], v[4:5] op_sel_hi:[1,0]
	v_pk_mul_f32 v[62:63], v[62:63], v[4:5] op_sel_hi:[1,0]
	v_pk_mul_f32 v[60:61], v[60:61], v[4:5] op_sel_hi:[1,0]
	v_pk_mul_f32 v[58:59], v[58:59], v[4:5] op_sel_hi:[1,0]
	v_pk_mul_f32 v[56:57], v[56:57], v[4:5] op_sel_hi:[1,0]
	v_pk_mul_f32 v[54:55], v[54:55], v[4:5] op_sel_hi:[1,0]
	v_pk_mul_f32 v[52:53], v[52:53], v[4:5] op_sel_hi:[1,0]
	v_pk_mul_f32 v[50:51], v[50:51], v[4:5] op_sel_hi:[1,0]
	v_pk_mul_f32 v[48:49], v[48:49], v[4:5] op_sel_hi:[1,0]
.LBB0_230:
	v_max_f32_e32 v4, v80, v81
	v_max3_f32 v4, v4, v82, v83
	v_max3_f32 v4, v4, v84, v85
	v_max3_f32 v4, v4, v86, v87
	v_max3_f32 v4, v4, v88, v89
	v_max3_f32 v4, v4, v90, v91
	v_max3_f32 v4, v4, v92, v93
	v_max3_f32 v4, v4, v94, v95
	v_mov_b32_e32 v5, v4
	s_nop 1
	v_permlane32_swap_b32_e32 v5, v4
	s_nop 1
	s_waitcnt lgkmcnt(0)
	v_max_f32_e32 v4, v4, v5
	v_add_f32_e32 v5, 0x41000000, v159
	v_cmp_gt_f32_e32 vcc, v4, v5
	s_cbranch_vccz .LBB0_232
	v_max_f32_e32 v5, v159, v4
	v_sub_f32_e32 v4, v159, v5
	v_exp_f32_e32 v4, v4
	v_mov_b32_e32 v159, v5
	v_mul_f32_e32 v162, v162, v4
	v_pk_mul_f32 v[46:47], v[46:47], v[4:5] op_sel_hi:[1,0]
	v_pk_mul_f32 v[44:45], v[44:45], v[4:5] op_sel_hi:[1,0]
	v_pk_mul_f32 v[42:43], v[42:43], v[4:5] op_sel_hi:[1,0]
	v_pk_mul_f32 v[40:41], v[40:41], v[4:5] op_sel_hi:[1,0]
	v_pk_mul_f32 v[38:39], v[38:39], v[4:5] op_sel_hi:[1,0]
	v_pk_mul_f32 v[36:37], v[36:37], v[4:5] op_sel_hi:[1,0]
	v_pk_mul_f32 v[34:35], v[34:35], v[4:5] op_sel_hi:[1,0]
	v_pk_mul_f32 v[32:33], v[32:33], v[4:5] op_sel_hi:[1,0]
	v_pk_mul_f32 v[30:31], v[30:31], v[4:5] op_sel_hi:[1,0]
	v_pk_mul_f32 v[28:29], v[28:29], v[4:5] op_sel_hi:[1,0]
	v_pk_mul_f32 v[26:27], v[26:27], v[4:5] op_sel_hi:[1,0]
	v_pk_mul_f32 v[24:25], v[24:25], v[4:5] op_sel_hi:[1,0]
	v_pk_mul_f32 v[22:23], v[22:23], v[4:5] op_sel_hi:[1,0]
	v_pk_mul_f32 v[20:21], v[20:21], v[4:5] op_sel_hi:[1,0]
	v_pk_mul_f32 v[18:19], v[18:19], v[4:5] op_sel_hi:[1,0]
	v_pk_mul_f32 v[16:17], v[16:17], v[4:5] op_sel_hi:[1,0]
.LBB0_232:
	v_sub_f32_e32 v4, v96, v1
	v_exp_f32_e32 v4, v4
	v_sub_f32_e32 v6, v97, v1
	v_exp_f32_e32 v6, v6
	v_sub_f32_e32 v7, v98, v1
	v_exp_f32_e32 v7, v7
	v_sub_f32_e32 v8, v99, v1
	v_exp_f32_e32 v8, v8
	v_add_f32_e32 v5, v6, v4
	v_add_f32_e32 v5, v7, v5
	v_add_f32_e32 v5, v8, v5
	v_cvt_pk_bf16_f32 v97, v7, v8
	v_sub_f32_e32 v8, v80, v159
	v_exp_f32_e32 v207, v8
	v_sub_f32_e32 v8, v81, v159
	v_exp_f32_e32 v209, v8
	v_sub_f32_e32 v8, v82, v159
	v_exp_f32_e32 v210, v8
	v_sub_f32_e32 v8, v83, v159
	v_exp_f32_e32 v211, v8
	v_sub_f32_e32 v8, v84, v159
	v_exp_f32_e32 v212, v8
	v_sub_f32_e32 v8, v85, v159
	v_exp_f32_e32 v213, v8
	v_sub_f32_e32 v8, v86, v159
	v_exp_f32_e32 v214, v8
	v_sub_f32_e32 v8, v87, v159
	v_exp_f32_e32 v215, v8
	v_sub_f32_e32 v8, v88, v159
	v_exp_f32_e32 v216, v8
	v_sub_f32_e32 v8, v89, v159
	v_lshl_add_u32 v204, v154, 1, v204
	v_exp_f32_e32 v217, v8
	v_sub_f32_e32 v8, v90, v159
	v_lshl_add_u32 v84, v164, 1, v204
	v_lshl_add_u32 v88, v163, 1, v204
	v_exp_f32_e32 v218, v8
	v_sub_f32_e32 v8, v91, v159
	ds_read_b64 v[222:223], v84 offset:8192
	ds_read_b64 v[226:227], v84 offset:12288
	ds_read_b64 v[224:225], v88 offset:8192
	ds_read_b64 v[228:229], v88 offset:12288
	v_exp_f32_e32 v219, v8
	v_sub_f32_e32 v8, v92, v159
	v_sub_f32_e32 v9, v100, v1
	v_sub_f32_e32 v96, v103, v1
	v_exp_f32_e32 v220, v8
	v_sub_f32_e32 v8, v93, v159
	v_exp_f32_e32 v9, v9
	v_sub_f32_e32 v10, v101, v1
	v_exp_f32_e32 v99, v96
	v_sub_f32_e32 v96, v104, v1
	v_exp_f32_e32 v205, v8
	v_sub_f32_e32 v8, v94, v159
	v_exp_f32_e32 v10, v10
	v_sub_f32_e32 v11, v102, v1
	v_exp_f32_e32 v100, v96
	v_sub_f32_e32 v96, v105, v1
	v_exp_f32_e32 v206, v8
	v_sub_f32_e32 v8, v95, v159
	s_waitcnt lgkmcnt(0)
	v_exp_f32_e32 v11, v11
	v_exp_f32_e32 v101, v96
	v_sub_f32_e32 v96, v106, v1
	v_exp_f32_e32 v102, v96
	v_sub_f32_e32 v96, v107, v1
	v_add_f32_e32 v5, v9, v5
	v_exp_f32_e32 v103, v96
	v_sub_f32_e32 v96, v108, v1
	v_add_f32_e32 v5, v10, v5
	v_exp_f32_e32 v104, v96
	v_sub_f32_e32 v96, v109, v1
	v_cvt_pk_bf16_f32 v80, v207, v209
	v_cvt_pk_bf16_f32 v81, v210, v211
	v_cvt_pk_bf16_f32 v82, v212, v213
	v_cvt_pk_bf16_f32 v83, v214, v215
	v_add_f32_e32 v5, v11, v5
	v_exp_f32_e32 v105, v96
	v_sub_f32_e32 v96, v110, v1
	v_mfma_f32_32x32x16_bf16 v[32:47], v[222:225], v[80:83], v[32:47]
	v_lshl_add_u32 v84, v160, 1, v204
	v_add_f32_e32 v5, v99, v5
	v_exp_f32_e32 v106, v96
	v_sub_f32_e32 v96, v111, v1
	ds_read_b64 v[232:233], v84 offset:8192
	ds_read_b64 v[236:237], v84 offset:12288
	v_add_f32_e32 v5, v100, v5
	v_exp_f32_e32 v107, v96
	v_mfma_f32_32x32x16_bf16 v[16:31], v[226:229], v[80:83], v[16:31]
	v_lshl_add_u32 v80, v161, 1, v204
	ds_read_b64 v[230:231], v80 offset:8192
	ds_read_b64 v[234:235], v80 offset:12288
	v_cvt_pk_bf16_f32 v96, v4, v6
	v_cvt_pk_bf16_f32 v98, v9, v10
	v_cvt_pk_bf16_f32 v99, v11, v99
	v_add_f32_e32 v5, v101, v5
	v_add_f32_e32 v5, v102, v5
	v_mfma_f32_32x32x16_bf16 v[64:79], v[222:225], v[96:99], v[64:79]
	v_add_f32_e32 v5, v103, v5
	v_add_f32_e32 v5, v104, v5
	v_add_f32_e32 v5, v105, v5
	v_add_f32_e32 v5, v106, v5
	v_add_f32_e32 v5, v107, v5
	v_add_f32_e32 v3, v3, v5
	v_cvt_pk_bf16_f32 v4, v100, v101
	v_mfma_f32_32x32x16_bf16 v[48:63], v[226:229], v[96:99], v[48:63]
	s_waitcnt lgkmcnt(0)
	v_cvt_pk_bf16_f32 v5, v102, v103
	v_cvt_pk_bf16_f32 v6, v104, v105
	v_cvt_pk_bf16_f32 v7, v106, v107
	v_exp_f32_e32 v208, v8
	v_cvt_pk_bf16_f32 v8, v216, v217
	v_mfma_f32_32x32x16_bf16 v[64:79], v[230:233], v[4:7], v[64:79]
	v_cvt_pk_bf16_f32 v9, v218, v219
	v_cvt_pk_bf16_f32 v10, v220, v205
	v_cvt_pk_bf16_f32 v11, v206, v208
	v_mfma_f32_32x32x16_bf16 v[48:63], v[234:237], v[4:7], v[48:63]
	ds_read_b128 v[4:7], v13 offset:4096
	v_mfma_f32_32x32x16_bf16 v[32:47], v[230:233], v[8:11], v[32:47]
	v_mfma_f32_32x32x16_bf16 v[16:31], v[234:237], v[8:11], v[16:31]
	s_waitcnt lgkmcnt(0)
	v_mfma_f32_32x32x16_bf16 v[96:111], v[4:7], v[136:139], 0
	v_mfma_f32_32x32x16_bf16 v[80:95], v[4:7], v[140:143], 0
	ds_read_b128 v[4:7], v14 offset:4096
	s_waitcnt lgkmcnt(0)
	v_mfma_f32_32x32x16_bf16 v[96:111], v[4:7], v[124:127], v[96:111]
	v_mfma_f32_32x32x16_bf16 v[80:95], v[4:7], v[132:135], v[80:95]
	ds_read_b128 v[4:7], v15 offset:4096
	s_waitcnt lgkmcnt(0)
	v_mfma_f32_32x32x16_bf16 v[96:111], v[4:7], v[120:123], v[96:111]
	v_mfma_f32_32x32x16_bf16 v[80:95], v[4:7], v[128:131], v[80:95]
	ds_read_b128 v[4:7], v12 offset:4096
	s_waitcnt lgkmcnt(0)
	v_mfma_f32_32x32x16_bf16 v[96:111], v[4:7], v[112:115], v[96:111]
	v_mfma_f32_32x32x16_bf16 v[80:95], v[4:7], v[116:119], v[80:95]
	s_nop 10
	v_max_f32_e32 v4, v96, v97
	v_max3_f32 v4, v4, v98, v99
	v_max3_f32 v4, v4, v100, v101
	v_max3_f32 v4, v4, v102, v103
	v_max3_f32 v4, v4, v104, v105
	v_max3_f32 v4, v4, v106, v107
	v_max3_f32 v4, v4, v108, v109
	v_max3_f32 v4, v4, v110, v111
	v_mov_b32_e32 v5, v4
	s_nop 1
	v_permlane32_swap_b32_e32 v5, v4
	s_nop 1
	s_waitcnt lgkmcnt(0)
	v_max_f32_e32 v4, v4, v5
	v_add_f32_e32 v5, 0x41000000, v1
	v_cmp_gt_f32_e32 vcc, v4, v5
	s_cbranch_vccz .LBB0_234
	v_max_f32_e32 v5, v1, v4
	v_sub_f32_e32 v1, v1, v5
	v_exp_f32_e32 v4, v1
	v_mov_b32_e32 v1, v5
	v_mul_f32_e32 v3, v3, v4
	v_pk_mul_f32 v[78:79], v[78:79], v[4:5] op_sel_hi:[1,0]
	v_pk_mul_f32 v[76:77], v[76:77], v[4:5] op_sel_hi:[1,0]
	v_pk_mul_f32 v[74:75], v[74:75], v[4:5] op_sel_hi:[1,0]
	v_pk_mul_f32 v[72:73], v[72:73], v[4:5] op_sel_hi:[1,0]
	v_pk_mul_f32 v[70:71], v[70:71], v[4:5] op_sel_hi:[1,0]
	v_pk_mul_f32 v[68:69], v[68:69], v[4:5] op_sel_hi:[1,0]
	v_pk_mul_f32 v[66:67], v[66:67], v[4:5] op_sel_hi:[1,0]
	v_pk_mul_f32 v[64:65], v[64:65], v[4:5] op_sel_hi:[1,0]
	v_pk_mul_f32 v[62:63], v[62:63], v[4:5] op_sel_hi:[1,0]
	v_pk_mul_f32 v[60:61], v[60:61], v[4:5] op_sel_hi:[1,0]
	v_pk_mul_f32 v[58:59], v[58:59], v[4:5] op_sel_hi:[1,0]
	v_pk_mul_f32 v[56:57], v[56:57], v[4:5] op_sel_hi:[1,0]
	v_pk_mul_f32 v[54:55], v[54:55], v[4:5] op_sel_hi:[1,0]
	v_pk_mul_f32 v[52:53], v[52:53], v[4:5] op_sel_hi:[1,0]
	v_pk_mul_f32 v[50:51], v[50:51], v[4:5] op_sel_hi:[1,0]
	v_pk_mul_f32 v[48:49], v[48:49], v[4:5] op_sel_hi:[1,0]
.LBB0_234:
	v_add_f32_e32 v4, v209, v207
	v_add_f32_e32 v4, v210, v4
	v_add_f32_e32 v4, v211, v4
	v_max_f32_e32 v5, v80, v81
	v_add_f32_e32 v4, v212, v4
	v_max3_f32 v5, v5, v82, v83
	v_add_f32_e32 v4, v213, v4
	v_max3_f32 v5, v5, v84, v85
	v_add_f32_e32 v4, v214, v4
	v_max3_f32 v5, v5, v86, v87
	v_add_f32_e32 v4, v215, v4
	v_max3_f32 v5, v5, v88, v89
	v_add_f32_e32 v4, v216, v4
	v_max3_f32 v5, v5, v90, v91
	v_add_f32_e32 v4, v217, v4
	v_max3_f32 v5, v5, v92, v93
	v_add_f32_e32 v4, v218, v4
	v_max3_f32 v5, v5, v94, v95
	v_add_f32_e32 v4, v219, v4
	v_mov_b32_e32 v6, v5
	s_nop 1
	v_permlane32_swap_b32_e32 v6, v5
	s_nop 1
	v_add_f32_e32 v4, v220, v4
	v_add_f32_e32 v4, v205, v4
	v_add_f32_e32 v4, v206, v4
	v_add_f32_e32 v4, v208, v4
	v_add_f32_e32 v8, v162, v4
	s_waitcnt lgkmcnt(0)
	v_max_f32_e32 v4, v5, v6
	v_add_f32_e32 v5, 0x41000000, v159
	v_cmp_gt_f32_e32 vcc, v4, v5
	s_cbranch_vccz .LBB0_225
	v_max_f32_e32 v5, v159, v4
	v_sub_f32_e32 v4, v159, v5
	v_exp_f32_e32 v4, v4
	v_mov_b32_e32 v159, v5
	v_mul_f32_e32 v8, v8, v4
	v_pk_mul_f32 v[46:47], v[46:47], v[4:5] op_sel_hi:[1,0]
	v_pk_mul_f32 v[44:45], v[44:45], v[4:5] op_sel_hi:[1,0]
	v_pk_mul_f32 v[42:43], v[42:43], v[4:5] op_sel_hi:[1,0]
	v_pk_mul_f32 v[40:41], v[40:41], v[4:5] op_sel_hi:[1,0]
	v_pk_mul_f32 v[38:39], v[38:39], v[4:5] op_sel_hi:[1,0]
	v_pk_mul_f32 v[36:37], v[36:37], v[4:5] op_sel_hi:[1,0]
	v_pk_mul_f32 v[34:35], v[34:35], v[4:5] op_sel_hi:[1,0]
	v_pk_mul_f32 v[32:33], v[32:33], v[4:5] op_sel_hi:[1,0]
	v_pk_mul_f32 v[30:31], v[30:31], v[4:5] op_sel_hi:[1,0]
	v_pk_mul_f32 v[28:29], v[28:29], v[4:5] op_sel_hi:[1,0]
	v_pk_mul_f32 v[26:27], v[26:27], v[4:5] op_sel_hi:[1,0]
	v_pk_mul_f32 v[24:25], v[24:25], v[4:5] op_sel_hi:[1,0]
	v_pk_mul_f32 v[22:23], v[22:23], v[4:5] op_sel_hi:[1,0]
	v_pk_mul_f32 v[20:21], v[20:21], v[4:5] op_sel_hi:[1,0]
	v_pk_mul_f32 v[18:19], v[18:19], v[4:5] op_sel_hi:[1,0]
	v_pk_mul_f32 v[16:17], v[16:17], v[4:5] op_sel_hi:[1,0]
	s_branch .LBB0_225
.LBB0_236:
	s_waitcnt vmcnt(0) lgkmcnt(0)
	s_barrier
	v_lshl_add_u32 v14, v203, 1, v165
	ds_read_b128 v[4:7], v14
	v_lshl_add_u32 v15, v202, 1, v165
	v_lshl_add_u32 v148, v201, 1, v165
	v_lshl_add_u32 v13, v167, 1, v165
	s_waitcnt lgkmcnt(0)
	v_mfma_f32_32x32x16_bf16 v[96:111], v[4:7], v[136:139], 0
	v_mfma_f32_32x32x16_bf16 v[80:95], v[4:7], v[140:143], 0
	ds_read_b128 v[4:7], v15
	s_waitcnt lgkmcnt(0)
	v_mfma_f32_32x32x16_bf16 v[96:111], v[4:7], v[124:127], v[96:111]
	v_mfma_f32_32x32x16_bf16 v[80:95], v[4:7], v[132:135], v[80:95]
	ds_read_b128 v[4:7], v148
	s_waitcnt lgkmcnt(0)
	v_mfma_f32_32x32x16_bf16 v[96:111], v[4:7], v[120:123], v[96:111]
	v_mfma_f32_32x32x16_bf16 v[80:95], v[4:7], v[128:131], v[80:95]
	ds_read_b128 v[4:7], v13
	s_waitcnt lgkmcnt(0)
	v_mfma_f32_32x32x16_bf16 v[96:111], v[4:7], v[112:115], v[96:111]
	v_mfma_f32_32x32x16_bf16 v[80:95], v[4:7], v[116:119], v[80:95]
	s_nop 10
	v_max_f32_e32 v4, v96, v97
	v_max3_f32 v4, v4, v98, v99
	v_max3_f32 v4, v4, v100, v101
	v_max3_f32 v4, v4, v102, v103
	v_max3_f32 v4, v4, v104, v105
	v_max3_f32 v4, v4, v106, v107
	v_max3_f32 v4, v4, v108, v109
	v_max3_f32 v4, v4, v110, v111
	v_mov_b32_e32 v5, v4
	s_nop 1
	v_permlane32_swap_b32_e32 v5, v4
	s_nop 1
	s_waitcnt lgkmcnt(0)
	v_max_f32_e32 v4, v4, v5
	v_add_f32_e32 v5, 0x41000000, v1
	v_cmp_gt_f32_e32 vcc, v4, v5
	s_cbranch_vccz .LBB0_238
	v_max_f32_e32 v5, v1, v4
	v_sub_f32_e32 v1, v1, v5
	v_exp_f32_e32 v4, v1
	v_mov_b32_e32 v1, v5
	v_mul_f32_e32 v3, v3, v4
	v_pk_mul_f32 v[78:79], v[78:79], v[4:5] op_sel_hi:[1,0]
	v_pk_mul_f32 v[76:77], v[76:77], v[4:5] op_sel_hi:[1,0]
	v_pk_mul_f32 v[74:75], v[74:75], v[4:5] op_sel_hi:[1,0]
	v_pk_mul_f32 v[72:73], v[72:73], v[4:5] op_sel_hi:[1,0]
	v_pk_mul_f32 v[70:71], v[70:71], v[4:5] op_sel_hi:[1,0]
	v_pk_mul_f32 v[68:69], v[68:69], v[4:5] op_sel_hi:[1,0]
	v_pk_mul_f32 v[66:67], v[66:67], v[4:5] op_sel_hi:[1,0]
	v_pk_mul_f32 v[64:65], v[64:65], v[4:5] op_sel_hi:[1,0]
	v_pk_mul_f32 v[62:63], v[62:63], v[4:5] op_sel_hi:[1,0]
	v_pk_mul_f32 v[60:61], v[60:61], v[4:5] op_sel_hi:[1,0]
	v_pk_mul_f32 v[58:59], v[58:59], v[4:5] op_sel_hi:[1,0]
	v_pk_mul_f32 v[56:57], v[56:57], v[4:5] op_sel_hi:[1,0]
	v_pk_mul_f32 v[54:55], v[54:55], v[4:5] op_sel_hi:[1,0]
	v_pk_mul_f32 v[52:53], v[52:53], v[4:5] op_sel_hi:[1,0]
	v_pk_mul_f32 v[50:51], v[50:51], v[4:5] op_sel_hi:[1,0]
	v_pk_mul_f32 v[48:49], v[48:49], v[4:5] op_sel_hi:[1,0]

.LBB0_240:
	v_sub_f32_e32 v4, v96, v1
	v_exp_f32_e32 v4, v4
	v_sub_f32_e32 v6, v97, v1
	v_exp_f32_e32 v6, v6
	v_sub_f32_e32 v7, v98, v1
	v_exp_f32_e32 v7, v7
	v_sub_f32_e32 v8, v99, v1
	v_exp_f32_e32 v8, v8
	v_sub_f32_e32 v9, v100, v1
	v_exp_f32_e32 v9, v9
	v_sub_f32_e32 v10, v101, v1
	v_add_f32_e32 v5, v6, v4
	v_exp_f32_e32 v10, v10
	v_sub_f32_e32 v11, v102, v1
	v_add_f32_e32 v5, v7, v5
	v_exp_f32_e32 v11, v11
	v_sub_f32_e32 v12, v103, v1
	v_add_f32_e32 v5, v8, v5
	v_exp_f32_e32 v99, v12
	v_sub_f32_e32 v12, v104, v1
	v_add_f32_e32 v5, v9, v5
	v_exp_f32_e32 v100, v12
	v_sub_f32_e32 v12, v105, v1
	v_add_f32_e32 v5, v10, v5
	v_exp_f32_e32 v101, v12
	v_sub_f32_e32 v12, v106, v1
	v_add_f32_e32 v5, v11, v5
	v_exp_f32_e32 v102, v12
	v_sub_f32_e32 v12, v107, v1
	v_add_f32_e32 v5, v99, v5
	v_exp_f32_e32 v103, v12
	v_sub_f32_e32 v12, v108, v1
	v_add_f32_e32 v5, v100, v5
	v_exp_f32_e32 v104, v12
	v_sub_f32_e32 v12, v109, v1
	v_add_f32_e32 v5, v101, v5
	v_exp_f32_e32 v105, v12
	v_sub_f32_e32 v12, v110, v1
	v_add_f32_e32 v5, v102, v5
	v_exp_f32_e32 v106, v12
	v_sub_f32_e32 v12, v111, v1
	v_add_f32_e32 v5, v103, v5
	v_exp_f32_e32 v107, v12
	v_add_f32_e32 v5, v104, v5
	v_add_f32_e32 v5, v105, v5
	v_add_f32_e32 v5, v106, v5
	v_add_f32_e32 v5, v107, v5
	v_add_f32_e32 v12, v3, v5
	v_sub_f32_e32 v3, v80, v159
	v_exp_f32_e32 v151, v3
	v_sub_f32_e32 v3, v81, v159
	v_exp_f32_e32 v153, v3
	v_sub_f32_e32 v3, v82, v159
	v_exp_f32_e32 v166, v3
	v_sub_f32_e32 v3, v83, v159
	v_exp_f32_e32 v167, v3
	v_sub_f32_e32 v3, v84, v159
	v_exp_f32_e32 v201, v3
	v_sub_f32_e32 v3, v85, v159
	v_exp_f32_e32 v202, v3
	v_sub_f32_e32 v3, v86, v159
	v_exp_f32_e32 v203, v3
	v_sub_f32_e32 v3, v87, v159
	v_exp_f32_e32 v204, v3
	v_sub_f32_e32 v3, v88, v159
	v_exp_f32_e32 v205, v3
	v_sub_f32_e32 v3, v89, v159
	v_exp_f32_e32 v206, v3
	v_sub_f32_e32 v3, v90, v159
	v_exp_f32_e32 v207, v3
	v_sub_f32_e32 v3, v91, v159
	v_exp_f32_e32 v208, v3
	v_sub_f32_e32 v3, v92, v159
	v_exp_f32_e32 v209, v3
	v_sub_f32_e32 v3, v93, v159
	v_exp_f32_e32 v149, v3
	v_sub_f32_e32 v3, v94, v159
	v_exp_f32_e32 v150, v3
	v_sub_f32_e32 v3, v95, v159
	v_exp_f32_e32 v152, v3
	v_lshl_add_u32 v3, v154, 1, v165
	v_lshl_add_u32 v84, v164, 1, v3
	v_lshl_add_u32 v88, v163, 1, v3
	ds_read_b64 v[222:223], v84 offset:8192
	ds_read_b64 v[226:227], v84 offset:12288
	ds_read_b64 v[224:225], v88 offset:8192
	ds_read_b64 v[228:229], v88 offset:12288
	v_cvt_pk_bf16_f32 v80, v151, v153
	v_cvt_pk_bf16_f32 v81, v166, v167
	v_cvt_pk_bf16_f32 v82, v201, v202
	s_waitcnt lgkmcnt(0)
	v_cvt_pk_bf16_f32 v83, v203, v204
	v_lshl_add_u32 v84, v160, 1, v3
	ds_read_b64 v[232:233], v84 offset:8192
	ds_read_b64 v[236:237], v84 offset:12288
	v_mfma_f32_32x32x16_bf16 v[32:47], v[222:225], v[80:83], v[32:47]
	v_cvt_pk_bf16_f32 v96, v4, v6
	v_cvt_pk_bf16_f32 v97, v7, v8
	v_cvt_pk_bf16_f32 v98, v9, v10
	v_cvt_pk_bf16_f32 v99, v11, v99
	v_cvt_pk_bf16_f32 v4, v100, v101
	v_cvt_pk_bf16_f32 v5, v102, v103
	v_cvt_pk_bf16_f32 v6, v104, v105
	v_mfma_f32_32x32x16_bf16 v[16:31], v[226:229], v[80:83], v[16:31]
	v_lshl_add_u32 v80, v161, 1, v3
	ds_read_b64 v[230:231], v80 offset:8192
	ds_read_b64 v[234:235], v80 offset:12288
	v_cvt_pk_bf16_f32 v7, v106, v107
	v_cvt_pk_bf16_f32 v8, v205, v206
	v_cvt_pk_bf16_f32 v9, v207, v208
	v_cvt_pk_bf16_f32 v10, v209, v149
	v_cvt_pk_bf16_f32 v11, v150, v152
	v_mfma_f32_32x32x16_bf16 v[64:79], v[222:225], v[96:99], v[64:79]
	v_mfma_f32_32x32x16_bf16 v[48:63], v[226:229], v[96:99], v[48:63]
	s_waitcnt lgkmcnt(0)
	v_mfma_f32_32x32x16_bf16 v[64:79], v[230:233], v[4:7], v[64:79]
	s_nop 0
	v_mfma_f32_32x32x16_bf16 v[48:63], v[234:237], v[4:7], v[48:63]
	ds_read_b128 v[4:7], v14 offset:4096
	v_mfma_f32_32x32x16_bf16 v[32:47], v[230:233], v[8:11], v[32:47]
	v_mfma_f32_32x32x16_bf16 v[16:31], v[234:237], v[8:11], v[16:31]
	s_waitcnt lgkmcnt(0)
	v_mfma_f32_32x32x16_bf16 v[96:111], v[4:7], v[136:139], 0
	v_mfma_f32_32x32x16_bf16 v[80:95], v[4:7], v[140:143], 0
	ds_read_b128 v[4:7], v15 offset:4096
	s_waitcnt lgkmcnt(0)
	v_mfma_f32_32x32x16_bf16 v[96:111], v[4:7], v[124:127], v[96:111]
	v_mfma_f32_32x32x16_bf16 v[80:95], v[4:7], v[132:135], v[80:95]
	ds_read_b128 v[4:7], v148 offset:4096
	s_waitcnt lgkmcnt(0)
	v_mfma_f32_32x32x16_bf16 v[96:111], v[4:7], v[120:123], v[96:111]
	v_mfma_f32_32x32x16_bf16 v[80:95], v[4:7], v[128:131], v[80:95]
	ds_read_b128 v[4:7], v13 offset:4096
	s_waitcnt lgkmcnt(0)
	v_mfma_f32_32x32x16_bf16 v[96:111], v[4:7], v[112:115], v[96:111]
	v_mfma_f32_32x32x16_bf16 v[80:95], v[4:7], v[116:119], v[80:95]
	s_nop 10
	v_max_f32_e32 v4, v96, v97
	v_max3_f32 v4, v4, v98, v99
	v_max3_f32 v4, v4, v100, v101
	v_max3_f32 v4, v4, v102, v103
	v_max3_f32 v4, v4, v104, v105
	v_max3_f32 v4, v4, v106, v107
	v_max3_f32 v4, v4, v108, v109
	v_max3_f32 v4, v4, v110, v111
	v_mov_b32_e32 v5, v4
	s_nop 1
	v_permlane32_swap_b32_e32 v5, v4
	s_nop 1
	s_waitcnt lgkmcnt(0)
	v_max_f32_e32 v4, v4, v5
	v_add_f32_e32 v5, 0x41000000, v1
	v_cmp_gt_f32_e32 vcc, v4, v5
	s_cbranch_vccz .LBB0_242
	v_max_f32_e32 v5, v1, v4
	v_sub_f32_e32 v1, v1, v5
	v_exp_f32_e32 v4, v1
	v_mov_b32_e32 v1, v5
	v_mul_f32_e32 v12, v12, v4
	v_pk_mul_f32 v[78:79], v[78:79], v[4:5] op_sel_hi:[1,0]
	v_pk_mul_f32 v[76:77], v[76:77], v[4:5] op_sel_hi:[1,0]
	v_pk_mul_f32 v[74:75], v[74:75], v[4:5] op_sel_hi:[1,0]
	v_pk_mul_f32 v[72:73], v[72:73], v[4:5] op_sel_hi:[1,0]
	v_pk_mul_f32 v[70:71], v[70:71], v[4:5] op_sel_hi:[1,0]
	v_pk_mul_f32 v[68:69], v[68:69], v[4:5] op_sel_hi:[1,0]
	v_pk_mul_f32 v[66:67], v[66:67], v[4:5] op_sel_hi:[1,0]
	v_pk_mul_f32 v[64:65], v[64:65], v[4:5] op_sel_hi:[1,0]
	v_pk_mul_f32 v[62:63], v[62:63], v[4:5] op_sel_hi:[1,0]
	v_pk_mul_f32 v[60:61], v[60:61], v[4:5] op_sel_hi:[1,0]
	v_pk_mul_f32 v[58:59], v[58:59], v[4:5] op_sel_hi:[1,0]
	v_pk_mul_f32 v[56:57], v[56:57], v[4:5] op_sel_hi:[1,0]
	v_pk_mul_f32 v[54:55], v[54:55], v[4:5] op_sel_hi:[1,0]
	v_pk_mul_f32 v[52:53], v[52:53], v[4:5] op_sel_hi:[1,0]
	v_pk_mul_f32 v[50:51], v[50:51], v[4:5] op_sel_hi:[1,0]
	v_pk_mul_f32 v[48:49], v[48:49], v[4:5] op_sel_hi:[1,0]
.LBB0_242:
	v_add_f32_e32 v4, v153, v151
	v_add_f32_e32 v4, v166, v4
	v_add_f32_e32 v4, v167, v4
	v_max_f32_e32 v5, v80, v81
	v_add_f32_e32 v4, v201, v4
	v_max3_f32 v5, v5, v82, v83
	v_add_f32_e32 v4, v202, v4
	v_max3_f32 v5, v5, v84, v85
	v_add_f32_e32 v4, v203, v4
	v_max3_f32 v5, v5, v86, v87
	v_add_f32_e32 v4, v204, v4
	v_max3_f32 v5, v5, v88, v89
	v_add_f32_e32 v4, v205, v4
	v_max3_f32 v5, v5, v90, v91
	v_add_f32_e32 v4, v206, v4
	v_max3_f32 v5, v5, v92, v93
	v_add_f32_e32 v4, v207, v4
	v_max3_f32 v5, v5, v94, v95
	v_add_f32_e32 v4, v208, v4
	v_mov_b32_e32 v6, v5
	s_nop 1
	v_permlane32_swap_b32_e32 v6, v5
	s_nop 1
	v_add_f32_e32 v4, v209, v4
	v_add_f32_e32 v4, v149, v4
	v_add_f32_e32 v4, v150, v4
	v_add_f32_e32 v4, v152, v4
	v_add_f32_e32 v8, v162, v4
	s_waitcnt lgkmcnt(0)
	v_max_f32_e32 v4, v5, v6
	v_add_f32_e32 v5, 0x41000000, v159
	v_cmp_gt_f32_e32 vcc, v4, v5
	s_cbranch_vccz .LBB0_244
	v_max_f32_e32 v5, v159, v4
	v_sub_f32_e32 v4, v159, v5
	v_exp_f32_e32 v4, v4
	v_mov_b32_e32 v159, v5
	v_mul_f32_e32 v8, v8, v4
	v_pk_mul_f32 v[46:47], v[46:47], v[4:5] op_sel_hi:[1,0]
	v_pk_mul_f32 v[44:45], v[44:45], v[4:5] op_sel_hi:[1,0]
	v_pk_mul_f32 v[42:43], v[42:43], v[4:5] op_sel_hi:[1,0]
	v_pk_mul_f32 v[40:41], v[40:41], v[4:5] op_sel_hi:[1,0]
	v_pk_mul_f32 v[38:39], v[38:39], v[4:5] op_sel_hi:[1,0]
	v_pk_mul_f32 v[36:37], v[36:37], v[4:5] op_sel_hi:[1,0]
	v_pk_mul_f32 v[34:35], v[34:35], v[4:5] op_sel_hi:[1,0]
	v_pk_mul_f32 v[32:33], v[32:33], v[4:5] op_sel_hi:[1,0]
	v_pk_mul_f32 v[30:31], v[30:31], v[4:5] op_sel_hi:[1,0]
	v_pk_mul_f32 v[28:29], v[28:29], v[4:5] op_sel_hi:[1,0]
	v_pk_mul_f32 v[26:27], v[26:27], v[4:5] op_sel_hi:[1,0]
	v_pk_mul_f32 v[24:25], v[24:25], v[4:5] op_sel_hi:[1,0]
	v_pk_mul_f32 v[22:23], v[22:23], v[4:5] op_sel_hi:[1,0]
	v_pk_mul_f32 v[20:21], v[20:21], v[4:5] op_sel_hi:[1,0]
	v_pk_mul_f32 v[18:19], v[18:19], v[4:5] op_sel_hi:[1,0]
	v_pk_mul_f32 v[16:17], v[16:17], v[4:5] op_sel_hi:[1,0]
